# sgu_unit: next-unit prefetch loads spread through the first part of the compute instead of issued in one burst; G==256 guard on the cross-unit pipelining
# baseline (speedup 1.0000x reference)
; __device__ __forceinline__ void sgu_unit(int chunk, int g, const bf16_t* ZUV, const float* SS2, const float* gn, const bf16_t* SGUW, const float* bs, bf16_t* MIX, LAS unsigned char* lds) {
;     ...
;     const int sr = tid & 127, qd = __builtin_amdgcn_readfirstlane(tid >> 7);
;     const bf16_t* zp = ZUV + (size_t)(r0 + sr) * 2048 + 1024 + g * 128 + qd * 32;
;     const bf16_t* wp = SGUW + (size_t)(g * 128 + t) * 128 + 8 * hi;
;     const bf16_t* zup = ZUV + (size_t)(r0 + t) * 2048 + g * 128;
;     u32x4 w[4]; f32x4 sq[4]; bf16x8 wvv[8]; u32x2 zav[4], zbv[4];
; #pragma unroll
;     for (int j = 0; j < 4; ++j) { w[j] = *(const u32x4*)(zp + j * 8); sq[j] = *(const f32x4*)(SS2 + (size_t)(r0 + sr) * 16 + 4 * j); }
; #pragma unroll
;     for (int ks = 0; ks < 8; ++ks) wvv[ks] = *(const bf16x8*)(wp + 16 * ks);
; #pragma unroll
;     for (int j = 0; j < 4; ++j) { zav[j] = *(const u32x2*)(zup + 32 * cb0 + 8 * j + 4 * hi); zbv[j] = *(const u32x2*)(zup + 32 * cb0 + 8 * j + 4 * hi + 32); }
.LBB0_249:
	v_mov_b32_e32 v0, v198
	v_mov_b32_e32 v2, s9
	v_readfirstlane_b32 s0, v0
	s_lshr_b32 s4, s0, 1
	v_and_b32_e32 v30, 31, v0
	s_and_b32 s4, s4, 0x60
	v_or_b32_e32 v6, s4, v30
	s_movk_i32 s4, 0x7f
	v_bfi_b32 v2, s4, v0, v2
	s_and_b32 s1, s9, 0xffffff80
	v_ashrrev_i32_e32 v3, 31, v2
	v_lshlrev_b64 v[4:5], 12, v[2:3]
	s_and_b32 s6, s8, 0x380
	s_ashr_i32 s0, s0, 2
	v_or_b32_e32 v80, s1, v6
	v_lshl_add_u64 v[4:5], s[54:55], 0, v[4:5]
	s_lshl_b32 s50, s6, 1
	s_and_b32 s4, s0, 0xffffffe0
	v_ashrrev_i32_e32 v81, 31, v80
	v_lshl_add_u64 v[4:5], v[4:5], 0, s[50:51]
	s_ashr_i32 s5, s4, 31
	v_or_b32_e32 v36, s6, v6
	v_lshlrev_b64 v[6:7], 12, v[80:81]
	v_lshl_add_u64 v[4:5], s[4:5], 1, v[4:5]
	v_lshl_add_u64 v[34:35], s[54:55], 0, v[6:7]
	v_lshlrev_b64 v[2:3], 6, v[2:3]
	s_andn2_b32 s0, s0, 63
	v_bfe_u32 v65, v0, 5, 1
	v_lshl_add_u64 v[2:3], s[16:17], 0, v[2:3]
	v_lshl_add_u64 v[238:239], v[4:5], 0, s[98:99]
	v_lshl_add_u64 v[240:241], v[2:3], 0, s[100:101]
	s_cmp_eq_u32 s10, s2
	s_cbranch_scc1 .Lsgu_ld1
	s_cmpk_eq_i32 s34, 0x100
	s_cbranch_scc1 .Lsgu_mov1
.Lsgu_ld1:
	global_load_dwordx4 v[6:9], v[4:5], off offset:2096
	global_load_dwordx4 v[10:13], v[4:5], off offset:2080
	global_load_dwordx4 v[14:17], v[4:5], off offset:2064
	global_load_dwordx4 v[18:21], v[4:5], off offset:2048
	global_load_dwordx4 v[22:25], v[2:3], off offset:48
	global_load_dwordx4 v[26:29], v[2:3], off offset:32
	global_load_dwordx4 v[82:85], v[2:3], off offset:16
	global_load_dwordx4 v[86:89], v[2:3], off
	s_branch .Lsgu_j1

; __device__ __forceinline__ void sgu_unit(int chunk, int g, const bf16_t* ZUV, const float* SS2, const float* gn, const bf16_t* SGUW, const float* bs, bf16_t* MIX, LAS unsigned char* lds) {
;     ...
;     const bf16_t* zp = ZUV + (size_t)(r0 + sr) * 2048 + 1024 + g * 128 + qd * 32;
;     const bf16_t* wp = SGUW + (size_t)(g * 128 + t) * 128 + 8 * hi;
;     const bf16_t* zup = ZUV + (size_t)(r0 + t) * 2048 + g * 128;
;     u32x4 w[4]; f32x4 sq[4]; bf16x8 wvv[8]; u32x2 zav[4], zbv[4];
; #pragma unroll
;     for (int j = 0; j < 4; ++j) { w[j] = *(const u32x4*)(zp + j * 8); sq[j] = *(const f32x4*)(SS2 + (size_t)(r0 + sr) * 16 + 4 * j); }
; #pragma unroll
;     for (int ks = 0; ks < 8; ++ks) wvv[ks] = *(const bf16x8*)(wp + 16 * ks);
; #pragma unroll
;     for (int j = 0; j < 4; ++j) { zav[j] = *(const u32x2*)(zup + 32 * cb0 + 8 * j + 4 * hi); zbv[j] = *(const u32x2*)(zup + 32 * cb0 + 8 * j + 4 * hi + 32); }
.Lsgu_j1:
	v_lshl_add_u64 v[4:5], v[34:35], 0, s[50:51]
	s_ashr_i32 s1, s0, 31
	v_and_b32_e32 v31, 0x7f, v0
	v_lshlrev_b32_e32 v0, 8, v36
	v_lshlrev_b32_e32 v32, 3, v65
	v_mov_b32_e32 v33, v1
	v_lshl_add_u64 v[4:5], s[0:1], 1, v[4:5]
	v_lshl_add_u64 v[2:3], s[12:13], 0, v[0:1]
	v_lshlrev_b32_e32 v0, 4, v65
	v_lshl_add_u64 v[4:5], v[4:5], 0, v[32:33]
	v_lshl_add_u64 v[2:3], v[2:3], 0, v[0:1]
	v_lshl_add_u64 v[242:243], v[4:5], 0, s[98:99]
	s_cmp_eq_u32 s10, s2
	s_cbranch_scc1 .Lsgu_ld2
	s_cmpk_eq_i32 s34, 0x100
	s_cbranch_scc1 .Lsgu_mov2
.Lsgu_ld2:
	global_load_dwordx2 v[78:79], v[4:5], off
	global_load_dwordx2 v[76:77], v[4:5], off offset:64
	global_load_dwordx2 v[74:75], v[4:5], off offset:16
	global_load_dwordx2 v[72:73], v[4:5], off offset:80
	global_load_dwordx2 v[70:71], v[4:5], off offset:32
	global_load_dwordx2 v[68:69], v[4:5], off offset:96
	global_load_dwordx2 v[66:67], v[4:5], off offset:48
	global_load_dwordx2 v[62:63], v[4:5], off offset:112
	s_branch .Lsgu_j2

; #define LAS __attribute__((address_space(3)))
; __device__ __forceinline__ unsigned pk_bf16(float lo, float hi) { const f32x2_t v = {lo, hi}; const bf16x2_t b = __builtin_convertvector(v, bf16x2_t); return __builtin_bit_cast(unsigned, b); }
; __device__ __forceinline__ float bf_lo(unsigned w) { return __uint_as_float(w << 16); }
; __device__ __forceinline__ float bf_hi(unsigned w) { return __uint_as_float(w & 0xffff0000u); }
; __device__ __forceinline__ void sgu_unit(int chunk, int g, const bf16_t* ZUV, const float* SS2, const float* gn, const bf16_t* SGUW, const float* bs, bf16_t* MIX, LAS unsigned char* lds) {
;     ...
;     for (int j = 0; j < 4; ++j) { w[j] = *(const u32x4*)(zp + j * 8); sq[j] = *(const f32x4*)(SS2 + (size_t)(r0 + sr) * 16 + 4 * j); }
; #pragma unroll
;     for (int ks = 0; ks < 8; ++ks) wvv[ks] = *(const bf16x8*)(wp + 16 * ks);
; #pragma unroll
;     for (int j = 0; j < 4; ++j) { zav[j] = *(const u32x2*)(zup + 32 * cb0 + 8 * j + 4 * hi); zbv[j] = *(const u32x2*)(zup + 32 * cb0 + 8 * j + 4 * hi + 32); }
;     const float bt = bs[g * 128 + t];
;     asm volatile("" : "+v"(w[0]), "+v"(w[1]), "+v"(w[2]), "+v"(w[3]), "+v"(sq[0]), "+v"(sq[1]), "+v"(sq[2]), "+v"(sq[3]),
;                  "+v"(wvv[0]), "+v"(wvv[1]), "+v"(wvv[2]), "+v"(wvv[3]), "+v"(wvv[4]), "+v"(wvv[5]), "+v"(wvv[6]), "+v"(wvv[7]),
;                  "+v"(zav[0]), "+v"(zav[1]), "+v"(zav[2]), "+v"(zav[3]), "+v"(zbv[0]), "+v"(zbv[1]), "+v"(zbv[2]), "+v"(zbv[3]) :: "memory");
;     {
;         const float sm = ((sq[0].x + sq[0].y) + (sq[0].z + sq[0].w)) + ((sq[1].x + sq[1].y) + (sq[1].z + sq[1].w)) + ((sq[2].x + sq[2].y) + (sq[2].z + sq[2].w)) + ((sq[3].x + sq[3].y) + (sq[3].z + sq[3].w));
;         const float rs = rsqrtf(sm * (1.0f / 1024.0f) + EPS);
; #pragma unroll
;         for (int j = 0; j < 4; ++j) {
;             const float* gp = gn + g * 128 + qd * 32 + j * 8; const f32x4 g0 = *(const f32x4*)gp, g1 = *(const f32x4*)(gp + 4);
;             const float v[8] = {bf_lo(w[j].x) * rs * g0.x, bf_hi(w[j].x) * rs * g0.y, bf_lo(w[j].y) * rs * g0.z, bf_hi(w[j].y) * rs * g0.w, bf_lo(w[j].z) * rs * g1.x, bf_hi(w[j].z) * rs * g1.y, bf_lo(w[j].w) * rs * g1.z, bf_hi(w[j].w) * rs * g1.w};
;             LAS bf16_t* zt = ZT + (qd * 32 + j * 8) * 136 + sr;
; #pragma unroll
;             for (int e = 0; e < 8; ++e) zt[e * 136] = (bf16_t)(pk_bf16(v[e], 0.f) & 0xffffu);
.Lsgu_j2:
	v_lshlrev_b32_e32 v4, 2, v36
	global_load_dword v64, v4, s[22:23]
	global_load_dwordx4 v[34:37], v[2:3], off offset:224
	global_load_dwordx4 v[38:41], v[2:3], off offset:192
	global_load_dwordx4 v[42:45], v[2:3], off offset:160
	global_load_dwordx4 v[46:49], v[2:3], off offset:128
	global_load_dwordx4 v[50:53], v[2:3], off offset:96
	global_load_dwordx4 v[54:57], v[2:3], off offset:64
	global_load_dwordx4 v[58:61], v[2:3], off offset:32
	s_nop 0
	global_load_dwordx4 v[2:5], v[2:3], off
	s_lshl_b32 s1, s6, 2
	s_add_u32 s1, s14, s1
	s_addc_u32 s11, s15, 0
	s_lshl_b64 s[6:7], s[4:5], 2
	s_add_u32 s6, s1, s6
	s_addc_u32 s7, s11, s7
	s_mul_i32 s1, s4, 0x110
	s_add_i32 s1, s1, 0
	v_lshl_add_u32 v31, v31, 1, s1
	s_add_i32 s10, s10, s34
	s_add_i32 s9, s9, s96
	s_add_i32 s8, s8, s20
	s_cmpk_gt_i32 s10, 0xfff
	global_load_dwordx4 v[206:209], v1, s[6:7]
	global_load_dwordx4 v[210:213], v1, s[6:7] offset:16
	global_load_dwordx4 v[214:217], v1, s[6:7] offset:32
	global_load_dwordx4 v[218:221], v1, s[6:7] offset:48
	global_load_dwordx4 v[222:225], v1, s[6:7] offset:64
	global_load_dwordx4 v[226:229], v1, s[6:7] offset:80
	global_load_dwordx4 v[230:233], v1, s[6:7] offset:96
	global_load_dwordx4 v[234:237], v1, s[6:7] offset:112
	s_waitcnt vmcnt(0)
	s_nop 0
	v_mov_b32_e32 v32, v87
	v_mov_b32_e32 v33, v88
	v_mov_b32_e32 v87, v89
	global_load_dwordx4 v[166:169], v[238:239], off offset:2096
	v_pk_add_f32 v[32:33], v[32:33], v[86:87]
	v_mov_b32_e32 v86, v83
	v_mov_b32_e32 v87, v84
	v_mov_b32_e32 v83, v85
	v_pk_add_f32 v[82:83], v[86:87], v[82:83]
	v_pk_add_f32 v[32:33], v[32:33], v[32:33] op_sel_hi:[0,1]
	global_load_dwordx4 v[170:173], v[238:239], off offset:2080
	v_pk_add_f32 v[82:83], v[82:83], v[82:83] op_sel_hi:[0,1]
	v_add_f32_e32 v27, v26, v27
	v_add_f32_e32 v29, v28, v29
	v_mov_b32_e32 v26, v22
	v_mov_b32_e32 v28, v23
	v_mov_b32_e32 v32, v24
	global_load_dwordx4 v[174:177], v[238:239], off offset:2064
	v_mov_b32_e32 v82, v25
	v_pk_add_f32 v[22:23], v[26:27], v[28:29]
	v_pk_add_f32 v[24:25], v[32:33], v[82:83]
	v_lshlrev_b32_e32 v33, 16, v18
	v_pk_add_f32 v[22:23], v[22:23], v[24:25]
	v_and_b32_e32 v18, 0xffff0000, v18
	global_load_dwordx4 v[178:181], v[238:239], off offset:2048
	v_add_f32_e32 v22, v22, v23
	v_fmamk_f32 v22, v22, 0x3a800000, v201
	v_cmp_gt_f32_e32 vcc, s57, v22
	v_mul_f32_e32 v23, 0x4b800000, v22
	s_nop 0
	v_cndmask_b32_e32 v22, v22, v23, vcc
	global_load_dwordx4 v[182:185], v[240:241], off offset:48
	v_rsq_f32_e32 v22, v22
	s_nop 0
	v_mul_f32_e32 v23, 0x45800000, v22
	v_cndmask_b32_e32 v32, v22, v23, vcc
	v_mul_f32_e32 v33, v32, v33
	v_mul_f32_e32 v18, v32, v18
	global_load_dwordx4 v[186:189], v[240:241], off offset:32
	v_mul_f32_e32 v33, v206, v33
	v_lshlrev_b32_e32 v86, 16, v19
	v_mul_f32_e32 v18, v207, v18
	v_mul_f32_e32 v86, v32, v86
	v_and_b32_e32 v19, 0xffff0000, v19
	v_mul_f32_e32 v86, v208, v86
	global_load_dwordx4 v[190:193], v[240:241], off offset:16
	v_mul_f32_e32 v19, v32, v19
	v_lshlrev_b32_e32 v87, 16, v20
	v_and_b32_e32 v20, 0xffff0000, v20
	v_cvt_pk_bf16_f32 v18, v18, s0
	v_mul_f32_e32 v19, v209, v19
	v_mul_f32_e32 v87, v32, v87
	global_load_dwordx4 v[194:197], v[240:241], off
	v_mul_f32_e32 v20, v32, v20
	ds_write_b16 v31, v18 offset:272
	v_cvt_pk_bf16_f32 v18, v86, s0
	v_mul_f32_e32 v82, v210, v87
	v_mul_f32_e32 v20, v211, v20
	v_lshlrev_b32_e32 v83, 16, v21
	global_load_dwordx2 v[244:245], v[242:243], off
	ds_write_b16 v31, v18 offset:544
	v_cvt_pk_bf16_f32 v18, v19, s0
	v_mul_f32_e32 v83, v32, v83
	v_and_b32_e32 v21, 0xffff0000, v21
	ds_write_b16 v31, v18 offset:816
	v_cvt_pk_bf16_f32 v18, v82, s0
	global_load_dwordx2 v[246:247], v[242:243], off offset:64
	v_mul_f32_e32 v83, v212, v83
	v_mul_f32_e32 v21, v32, v21
	ds_write_b16 v31, v18 offset:1088
	v_cvt_pk_bf16_f32 v18, v20, s0
	v_mul_f32_e32 v21, v213, v21
	ds_write_b16 v31, v18 offset:1360
	global_load_dwordx2 v[248:249], v[242:243], off offset:16
	v_cvt_pk_bf16_f32 v18, v83, s0
	ds_write_b16 v31, v18 offset:1632
	v_cvt_pk_bf16_f32 v18, v21, s0
	ds_write_b16 v31, v18 offset:1904
	v_lshlrev_b32_e32 v18, 16, v14
	v_and_b32_e32 v14, 0xffff0000, v14
	global_load_dwordx2 v[250:251], v[242:243], off offset:80
	v_mul_f32_e32 v14, v32, v14
	v_lshlrev_b32_e32 v19, 16, v15
	v_mul_f32_e32 v14, v215, v14
	v_mul_f32_e32 v19, v32, v19
	v_and_b32_e32 v15, 0xffff0000, v15
	v_mul_f32_e32 v19, v216, v19
	global_load_dwordx2 v[124:125], v[242:243], off offset:32
	v_mul_f32_e32 v15, v32, v15
	v_lshlrev_b32_e32 v20, 16, v16
	v_cvt_pk_bf16_f32 v14, v14, s0
	v_mul_f32_e32 v15, v217, v15
	v_mul_f32_e32 v20, v32, v20
	v_and_b32_e32 v16, 0xffff0000, v16
	global_load_dwordx2 v[126:127], v[242:243], off offset:96
	ds_write_b16 v31, v14 offset:2448
	v_cvt_pk_bf16_f32 v14, v19, s0
	v_mul_f32_e32 v20, v218, v20
	v_mul_f32_e32 v16, v32, v16
	v_lshlrev_b32_e32 v21, 16, v17
	ds_write_b16 v31, v14 offset:2720
	global_load_dwordx2 v[128:129], v[242:243], off offset:48
	v_cvt_pk_bf16_f32 v14, v15, s0
	v_mul_f32_e32 v16, v219, v16
	v_mul_f32_e32 v21, v32, v21
	v_and_b32_e32 v17, 0xffff0000, v17
	ds_write_b16 v31, v14 offset:2992
	v_cvt_pk_bf16_f32 v14, v20, s0
	global_load_dwordx2 v[158:159], v[242:243], off offset:112
	v_mul_f32_e32 v18, v32, v18
	v_mul_f32_e32 v21, v220, v21
	v_mul_f32_e32 v17, v32, v17
	ds_write_b16 v31, v14 offset:3264
	v_cvt_pk_bf16_f32 v14, v16, s0
	v_mul_f32_e32 v18, v214, v18
	v_mul_f32_e32 v17, v221, v17
	ds_write_b16 v31, v14 offset:3536
	v_cvt_pk_bf16_f32 v14, v21, s0
	v_cvt_pk_bf16_f32 v33, v33, s0
	v_cvt_pk_bf16_f32 v18, v18, s0
	ds_write_b16 v31, v14 offset:3808
	v_cvt_pk_bf16_f32 v14, v17, s0
	ds_write_b16 v31, v33
	ds_write_b16 v31, v18 offset:2176
; #define LAS __attribute__((address_space(3)))
; __device__ __forceinline__ unsigned pk_bf16(float lo, float hi) { const f32x2_t v = {lo, hi}; const bf16x2_t b = __builtin_convertvector(v, bf16x2_t); return __builtin_bit_cast(unsigned, b); }
; __device__ __forceinline__ float bf_lo(unsigned w) { return __uint_as_float(w << 16); }
; __device__ __forceinline__ float bf_hi(unsigned w) { return __uint_as_float(w & 0xffff0000u); }
; __device__ __forceinline__ void sgu_unit(int chunk, int g, const bf16_t* ZUV, const float* SS2, const float* gn, const bf16_t* SGUW, const float* bs, bf16_t* MIX, LAS unsigned char* lds) {
;     ...
; #pragma unroll
;         for (int j = 0; j < 4; ++j) {
;             const float* gp = gn + g * 128 + qd * 32 + j * 8; const f32x4 g0 = *(const f32x4*)gp, g1 = *(const f32x4*)(gp + 4);
;             const float v[8] = {bf_lo(w[j].x) * rs * g0.x, bf_hi(w[j].x) * rs * g0.y, bf_lo(w[j].y) * rs * g0.z, bf_hi(w[j].y) * rs * g0.w, bf_lo(w[j].z) * rs * g1.x, bf_hi(w[j].z) * rs * g1.y, bf_lo(w[j].w) * rs * g1.z, bf_hi(w[j].w) * rs * g1.w};
;             LAS bf16_t* zt = ZT + (qd * 32 + j * 8) * 136 + sr;
; #pragma unroll
;             for (int e = 0; e < 8; ++e) zt[e * 136] = (bf16_t)(pk_bf16(v[e], 0.f) & 0xffffu);
;         }
;     }
;     __syncthreads();
	ds_write_b16 v31, v14 offset:4080
	v_lshlrev_b32_e32 v33, 16, v10
	v_and_b32_e32 v10, 0xffff0000, v10
	v_mul_f32_e32 v10, v32, v10
	v_mul_f32_e32 v33, v32, v33
	v_mul_f32_e32 v10, v10, v223
	v_lshlrev_b32_e32 v27, 16, v11
	v_mul_f32_e32 v27, v32, v27
	v_and_b32_e32 v11, 0xffff0000, v11
	v_mul_f32_e32 v27, v27, v224
	v_mul_f32_e32 v11, v32, v11
	v_lshlrev_b32_e32 v28, 16, v12
	v_and_b32_e32 v12, 0xffff0000, v12
	v_cvt_pk_bf16_f32 v10, v10, s0
	v_mul_f32_e32 v11, v11, v225
	v_mul_f32_e32 v28, v32, v28
	v_mul_f32_e32 v12, v32, v12
	ds_write_b16 v31, v10 offset:4624
	v_cvt_pk_bf16_f32 v10, v27, s0
	v_mul_f32_e32 v22, v28, v226
	v_mul_f32_e32 v12, v12, v227
	v_lshlrev_b32_e32 v23, 16, v13
	ds_write_b16 v31, v10 offset:4896
	v_cvt_pk_bf16_f32 v10, v11, s0
	v_mul_f32_e32 v23, v32, v23
	v_and_b32_e32 v13, 0xffff0000, v13
	ds_write_b16 v31, v10 offset:5168
	v_cvt_pk_bf16_f32 v10, v22, s0
	v_mul_f32_e32 v23, v23, v228
	v_mul_f32_e32 v13, v32, v13
	ds_write_b16 v31, v10 offset:5440
	v_cvt_pk_bf16_f32 v10, v12, s0
	v_mul_f32_e32 v13, v13, v229
	ds_write_b16 v31, v10 offset:5712
	v_cvt_pk_bf16_f32 v10, v23, s0
	ds_write_b16 v31, v10 offset:5984
	v_cvt_pk_bf16_f32 v10, v13, s0
	ds_write_b16 v31, v10 offset:6256
	v_lshlrev_b32_e32 v10, 16, v6
	v_and_b32_e32 v6, 0xffff0000, v6
	v_mul_f32_e32 v6, v32, v6
	v_lshlrev_b32_e32 v11, 16, v7
	v_mul_f32_e32 v6, v6, v231
	v_mul_f32_e32 v11, v32, v11
	v_and_b32_e32 v7, 0xffff0000, v7
	v_mul_f32_e32 v11, v11, v232
	v_mul_f32_e32 v7, v32, v7
	v_lshlrev_b32_e32 v12, 16, v8
	v_cvt_pk_bf16_f32 v6, v6, s0
	v_mul_f32_e32 v7, v7, v233
	v_mul_f32_e32 v12, v32, v12
	v_and_b32_e32 v8, 0xffff0000, v8
	ds_write_b16 v31, v6 offset:6800
	v_cvt_pk_bf16_f32 v6, v11, s0
	v_mul_f32_e32 v12, v12, v234
	v_mul_f32_e32 v8, v32, v8
	v_lshlrev_b32_e32 v13, 16, v9
	ds_write_b16 v31, v6 offset:7072
	v_cvt_pk_bf16_f32 v6, v7, s0
	v_mul_f32_e32 v8, v8, v235
	v_mul_f32_e32 v13, v32, v13
	v_and_b32_e32 v9, 0xffff0000, v9
	ds_write_b16 v31, v6 offset:7344
	v_cvt_pk_bf16_f32 v6, v12, s0
	v_mul_f32_e32 v13, v13, v236
	v_mul_f32_e32 v9, v32, v9
	ds_write_b16 v31, v6 offset:7616
	v_cvt_pk_bf16_f32 v6, v8, s0
	v_mul_f32_e32 v9, v9, v237
	ds_write_b16 v31, v6 offset:7888
	v_cvt_pk_bf16_f32 v6, v13, s0
	ds_write_b16 v31, v6 offset:8160
	v_cvt_pk_bf16_f32 v6, v9, s0
	v_mul_f32_e32 v10, v32, v10
	ds_write_b16 v31, v6 offset:8432
	v_or_b32_e32 v6, s0, v30
	v_mul_f32_e32 v26, v33, v222
	v_mul_f32_e32 v10, v10, v230
	v_mul_lo_u32 v6, v6, s21
	v_cvt_pk_bf16_f32 v24, v26, s0
	v_cvt_pk_bf16_f32 v10, v10, s0
	v_add3_u32 v0, 0, v6, v0
	ds_write_b16 v31, v24 offset:4352
	ds_write_b16 v31, v10 offset:6528
	s_waitcnt lgkmcnt(0)
	s_barrier
; #define LAS __attribute__((address_space(3)))
; __device__ __forceinline__ unsigned pk_bf16(float lo, float hi) { const f32x2_t v = {lo, hi}; const bf16x2_t b = __builtin_convertvector(v, bf16x2_t); return __builtin_bit_cast(unsigned, b); }
; __device__ __forceinline__ float bf_lo(unsigned w) { return __uint_as_float(w << 16); }
; __device__ __forceinline__ float bf_hi(unsigned w) { return __uint_as_float(w & 0xffff0000u); }
; __device__ __forceinline__ void sgu_unit(int chunk, int g, const bf16_t* ZUV, const float* SS2, const float* gn, const bf16_t* SGUW, const float* bs, bf16_t* MIX, LAS unsigned char* lds) {
;     ...
;     f32x16 d0, d1;
; #pragma unroll
;     for (int r = 0; r < 16; ++r) { d0[r] = 0.f; d1[r] = 0.f; }
; #pragma unroll
;     for (int ks = 0; ks < 8; ++ks) {
;         const bf16x8 z0 = *(const LAS bf16x8*)(ZT + (32 * cb0 + q32) * 136 + 16 * ks + 8 * hi);
;         const bf16x8 z1 = *(const LAS bf16x8*)(ZT + (32 * (cb0 + 1) + q32) * 136 + 16 * ks + 8 * hi);
;         d0 = __builtin_amdgcn_mfma_f32_32x32x16_bf16(z0, wvv[ks], d0, 0, 0, 0);
;         d1 = __builtin_amdgcn_mfma_f32_32x32x16_bf16(z1, wvv[ks], d1, 0, 0, 0);
;     }
;     bf16_t* op = MIX + (size_t)(r0 + t) * DM + g * 128;
; #pragma unroll
;     for (int j = 0; j < 4; ++j) {
;         const int c0 = 32 * cb0 + 8 * j + 4 * hi, c1 = c0 + 32;
;         const u32x2 za = zav[j], zb = zbv[j];
;         u32x2 wa, wb;
;         wa.x = pk_bf16(bf_lo(za.x) * (d0[4 * j + 0] + bt), bf_hi(za.x) * (d0[4 * j + 1] + bt)); wa.y = pk_bf16(bf_lo(za.y) * (d0[4 * j + 2] + bt), bf_hi(za.y) * (d0[4 * j + 3] + bt));
;         wb.x = pk_bf16(bf_lo(zb.x) * (d1[4 * j + 0] + bt), bf_hi(zb.x) * (d1[4 * j + 1] + bt)); wb.y = pk_bf16(bf_lo(zb.y) * (d1[4 * j + 2] + bt), bf_hi(zb.y) * (d1[4 * j + 3] + bt));
;         *(u32x2*)(op + c0) = wa; *(u32x2*)(op + c1) = wb;
;     }
;     __syncthreads();
	ds_read_b128 v[6:9], v0 offset:8704
	ds_read_b128 v[10:13], v0
	ds_read_b128 v[82:85], v0 offset:32
	s_waitcnt lgkmcnt(1)
	v_mfma_f32_32x32x16_bf16 v[18:33], v[10:13], v[2:5], 0
	ds_read_b128 v[86:89], v0 offset:8736
	v_mfma_f32_32x32x16_bf16 v[2:17], v[6:9], v[2:5], 0
	s_waitcnt lgkmcnt(1)
	v_mfma_f32_32x32x16_bf16 v[18:33], v[82:85], v[58:61], v[18:33]
	s_waitcnt lgkmcnt(0)
	v_mfma_f32_32x32x16_bf16 v[2:17], v[86:89], v[58:61], v[2:17]
	ds_read_b128 v[58:61], v0 offset:64
	ds_read_b128 v[82:85], v0 offset:8768
	s_waitcnt lgkmcnt(1)
	v_mfma_f32_32x32x16_bf16 v[18:33], v[58:61], v[54:57], v[18:33]
	s_waitcnt lgkmcnt(0)
	v_mfma_f32_32x32x16_bf16 v[2:17], v[82:85], v[54:57], v[2:17]
	ds_read_b128 v[54:57], v0 offset:96
	ds_read_b128 v[58:61], v0 offset:8800
	s_waitcnt lgkmcnt(1)
	v_mfma_f32_32x32x16_bf16 v[18:33], v[54:57], v[50:53], v[18:33]
	s_waitcnt lgkmcnt(0)
	v_mfma_f32_32x32x16_bf16 v[2:17], v[58:61], v[50:53], v[2:17]
	ds_read_b128 v[50:53], v0 offset:128
	ds_read_b128 v[54:57], v0 offset:8832
	s_waitcnt lgkmcnt(1)
	v_mfma_f32_32x32x16_bf16 v[18:33], v[50:53], v[46:49], v[18:33]
	s_waitcnt lgkmcnt(0)
	v_mfma_f32_32x32x16_bf16 v[2:17], v[54:57], v[46:49], v[2:17]
	ds_read_b128 v[46:49], v0 offset:160
	ds_read_b128 v[50:53], v0 offset:8864
	s_waitcnt lgkmcnt(1)
	v_mfma_f32_32x32x16_bf16 v[18:33], v[46:49], v[42:45], v[18:33]
	s_waitcnt lgkmcnt(0)
	v_mfma_f32_32x32x16_bf16 v[2:17], v[50:53], v[42:45], v[2:17]
	ds_read_b128 v[42:45], v0 offset:192
	ds_read_b128 v[46:49], v0 offset:8896
	s_waitcnt lgkmcnt(1)
	v_mfma_f32_32x32x16_bf16 v[18:33], v[42:45], v[38:41], v[18:33]
	s_waitcnt lgkmcnt(0)
	v_mfma_f32_32x32x16_bf16 v[2:17], v[46:49], v[38:41], v[2:17]
	ds_read_b128 v[38:41], v0 offset:224
	ds_read_b128 v[42:45], v0 offset:8928
	s_waitcnt lgkmcnt(1)
	v_mfma_f32_32x32x16_bf16 v[18:33], v[38:41], v[34:37], v[18:33]
	v_lshlrev_b32_e32 v38, 16, v78
	v_and_b32_e32 v39, 0xffff0000, v78
	s_waitcnt lgkmcnt(0)
	v_mfma_f32_32x32x16_bf16 v[2:17], v[42:45], v[34:37], v[2:17]
	s_nop 7
	v_add_f32_e64 v18, v64, v18
	v_add_f32_e64 v19, v64, v19
	v_mul_f32_e64 v18, v18, v38
	v_mul_f32_e64 v19, v19, v39
	v_lshlrev_b32_e32 v38, 16, v79
	v_and_b32_e32 v39, 0xffff0000, v79
	v_pk_add_f32 v[20:21], v[64:65], v[20:21] op_sel_hi:[0,1]
	v_pk_mul_f32 v[20:21], v[20:21], v[38:39]
	v_lshlrev_b64 v[34:35], 11, v[80:81]
	v_cvt_pk_bf16_f32 v18, v18, v19
	v_cvt_pk_bf16_f32 v19, v20, v21
	v_lshlrev_b32_e32 v20, 16, v76
	v_and_b32_e32 v21, 0xffff0000, v76
	v_pk_add_f32 v[2:3], v[64:65], v[2:3] op_sel_hi:[0,1]
	v_lshl_add_u64 v[34:35], s[52:53], 0, v[34:35]
	v_lshl_or_b32 v36, v65, 2, s0
	v_pk_mul_f32 v[2:3], v[2:3], v[20:21]
	v_lshlrev_b32_e32 v20, 16, v77
	v_and_b32_e32 v21, 0xffff0000, v77
	v_pk_add_f32 v[4:5], v[64:65], v[4:5] op_sel_hi:[0,1]
	v_lshl_add_u64 v[34:35], v[34:35], 0, s[50:51]
	v_pk_mul_f32 v[4:5], v[4:5], v[20:21]
	v_ashrrev_i32_e32 v37, 31, v36
	v_cvt_pk_bf16_f32 v2, v2, v3
	v_cvt_pk_bf16_f32 v3, v4, v5
	v_lshl_add_u64 v[4:5], v[36:37], 1, v[34:35]
	global_store_dwordx2 v[4:5], v[18:19], off
	global_store_dwordx2 v[4:5], v[2:3], off offset:64
	v_lshlrev_b32_e32 v2, 16, v74
	v_and_b32_e32 v3, 0xffff0000, v74
	v_pk_add_f32 v[18:19], v[64:65], v[22:23] op_sel_hi:[0,1]
	v_pk_mul_f32 v[2:3], v[18:19], v[2:3]
	v_lshlrev_b32_e32 v18, 16, v75
	v_and_b32_e32 v19, 0xffff0000, v75
	v_pk_add_f32 v[20:21], v[64:65], v[24:25] op_sel_hi:[0,1]
	v_pk_mul_f32 v[18:19], v[20:21], v[18:19]
	v_cvt_pk_bf16_f32 v2, v2, v3
	v_cvt_pk_bf16_f32 v3, v18, v19
	v_lshlrev_b32_e32 v18, 16, v72
	v_and_b32_e32 v19, 0xffff0000, v72
	v_pk_add_f32 v[6:7], v[64:65], v[6:7] op_sel_hi:[0,1]
	v_pk_mul_f32 v[6:7], v[6:7], v[18:19]
	v_lshlrev_b32_e32 v18, 16, v73
	v_and_b32_e32 v19, 0xffff0000, v73
	v_pk_add_f32 v[8:9], v[64:65], v[8:9] op_sel_hi:[0,1]
	v_pk_mul_f32 v[8:9], v[8:9], v[18:19]
	v_cvt_pk_bf16_f32 v6, v6, v7
	v_cvt_pk_bf16_f32 v7, v8, v9
	global_store_dwordx2 v[4:5], v[2:3], off offset:16
	global_store_dwordx2 v[4:5], v[6:7], off offset:80
	v_lshlrev_b32_e32 v2, 16, v70
	v_and_b32_e32 v3, 0xffff0000, v70
	v_pk_add_f32 v[6:7], v[64:65], v[26:27] op_sel_hi:[0,1]
	v_pk_mul_f32 v[2:3], v[6:7], v[2:3]
	v_lshlrev_b32_e32 v6, 16, v71
	v_and_b32_e32 v7, 0xffff0000, v71
	v_pk_add_f32 v[8:9], v[64:65], v[28:29] op_sel_hi:[0,1]
	v_pk_mul_f32 v[6:7], v[8:9], v[6:7]
	v_cvt_pk_bf16_f32 v2, v2, v3
	v_cvt_pk_bf16_f32 v3, v6, v7
	v_lshlrev_b32_e32 v6, 16, v68
	v_and_b32_e32 v7, 0xffff0000, v68
	v_pk_add_f32 v[8:9], v[64:65], v[10:11] op_sel_hi:[0,1]
	v_pk_mul_f32 v[6:7], v[8:9], v[6:7]
	v_lshlrev_b32_e32 v8, 16, v69
	v_and_b32_e32 v9, 0xffff0000, v69
	v_pk_add_f32 v[10:11], v[64:65], v[12:13] op_sel_hi:[0,1]
	v_pk_mul_f32 v[8:9], v[10:11], v[8:9]
	v_cvt_pk_bf16_f32 v6, v6, v7
	v_cvt_pk_bf16_f32 v7, v8, v9
	global_store_dwordx2 v[4:5], v[2:3], off offset:32
	global_store_dwordx2 v[4:5], v[6:7], off offset:96
	v_lshlrev_b32_e32 v2, 16, v66
	v_and_b32_e32 v3, 0xffff0000, v66
	v_pk_add_f32 v[6:7], v[64:65], v[30:31] op_sel_hi:[0,1]
	v_pk_mul_f32 v[2:3], v[6:7], v[2:3]
	v_lshlrev_b32_e32 v6, 16, v67
	v_and_b32_e32 v7, 0xffff0000, v67
	v_pk_add_f32 v[8:9], v[64:65], v[32:33] op_sel_hi:[0,1]
	v_pk_mul_f32 v[6:7], v[8:9], v[6:7]
	v_cvt_pk_bf16_f32 v2, v2, v3
	v_cvt_pk_bf16_f32 v3, v6, v7
	v_lshlrev_b32_e32 v6, 16, v62
	v_and_b32_e32 v7, 0xffff0000, v62
	v_pk_add_f32 v[8:9], v[64:65], v[14:15] op_sel_hi:[0,1]
	v_pk_mul_f32 v[6:7], v[8:9], v[6:7]
	v_lshlrev_b32_e32 v8, 16, v63
	v_and_b32_e32 v9, 0xffff0000, v63
	v_pk_add_f32 v[10:11], v[64:65], v[16:17] op_sel_hi:[0,1]
	v_pk_mul_f32 v[8:9], v[10:11], v[8:9]
	v_cvt_pk_bf16_f32 v6, v6, v7
	v_cvt_pk_bf16_f32 v7, v8, v9
	global_store_dwordx2 v[4:5], v[2:3], off offset:48
	global_store_dwordx2 v[4:5], v[6:7], off offset:112
	s_barrier
	s_cbranch_scc0 .LBB0_249
